# adds: HGRN half-steps issue the raw-row LDS reads before the next-step staging DMA
# baseline (speedup 1.0000x reference)
; #define LAS __attribute__((address_space(3)))
; __device__ __forceinline__ unsigned cvtpk(float lo, float hi) { f32x2_t v = {lo, hi}; bf16x2_t b = __builtin_convertvector(v, bf16x2_t); return __builtin_bit_cast(unsigned, b); }
; __device__ __forceinline__ void prep(const Raw& Rin, LAS unsigned char* buf, int lane, int kch, int tq, bool isv, int vv, int vtq) {
;     Raw R = Rin; const bool kodd = kch & 1, vodd = vv & 1;
; #pragma unroll
;     for (int i = 0; i < 4; ++i) { asm volatile("" : "+v"(R.q[i])); asm volatile("" : "+v"(R.f[i])); asm volatile("" : "+v"(R.v[i])); }
;     float qv[4], kk[4], c[4]; float run = 0.f;
; #pragma unroll
;     for (int i = 0; i < 4; ++i) {
;         qv[i] = __uint_as_float(kodd ? (R.q[i] & 0xffff0000u) : (R.q[i] << 16));
;         const float l2 = __uint_as_float(kodd ? (R.f[i] & 0xffff0000u) : (R.f[i] << 16));
;         kk[i] = 1.f - __builtin_amdgcn_exp2f(l2);
;         run += l2; c[i] = run;
;     }
;     const float p1 = __shfl(run, (lane - 16) & 63), p2 = __shfl(run, (lane - 32) & 63), p3 = __shfl(run, (lane - 48) & 63);
;     const float off = (tq >= 1 ? p1 : 0.f) + (tq >= 2 ? p2 : 0.f) + (tq >= 3 ? p3 : 0.f);
;     const float btot = __shfl(off + run, 48 + (lane & 15));
;     unsigned short kf[4];
; #pragma unroll
;     for (int i = 0; i < 4; ++i) {
;         const float bt = off + c[i];
;         const float qf = qv[i] * __builtin_amdgcn_exp2f(bt), kfv = kk[i] * __builtin_amdgcn_exp2f(-bt);
;         const unsigned pk = cvtpk(qf, kfv);
;         *(LAS unsigned short*)(buf + OFF_QF + (4 * tq + i) * STR + kch * 2) = (unsigned short)(pk & 0xffffu);
;         kf[i] = (unsigned short)(pk >> 16);
;         *(LAS unsigned short*)(buf + OFF_KF + (4 * tq + i) * STR + kch * 2) = kf[i];
;     }
;     *(LAS u32x2*)(buf + OFF_KFT + kch * 32 + tq * 8) = (u32x2){(unsigned)kf[0] | ((unsigned)kf[1] << 16), (unsigned)kf[2] | ((unsigned)kf[3] << 16)};
;     if (tq == 0) *(LAS float*)(buf + OFF_D + kch * 4) = __builtin_amdgcn_exp2f(btot);
.LBB0_625:
	s_add_i32 s41, s7, 1
	s_and_b32 s41, s41, 3
	s_mul_i32 s41, s41, 9792
	v_add_u32_e32 v140, s41, v136
	v_add_u32_e32 v141, s41, v137
	v_add_u32_e32 v153, 0x1100, v140
	ds_read2_b32 v[156:157], v153 offset1:64
	ds_read2_b32 v[158:159], v153 offset0:128 offset1:192
	ds_read2_b32 v[160:161], v140 offset1:64
	ds_read2_b32 v[162:163], v140 offset0:128 offset1:192
	ds_read2_b32 v[40:41], v141 offset1:16
	ds_read2_b32 v[164:165], v141 offset0:32 offset1:48
	s_add_i32 s41, s7, 4
	s_min_u32 s41, s41, 0x7f
	s_mul_i32 s41, s41, 0x1d400
	s_add_u32 s42, s38, s41
	s_addc_u32 s43, s39, 0
	s_add_i32 s41, s7, 0
	s_and_b32 s41, s41, 3
	s_mul_i32 s41, s41, 9792
	s_add_i32 m0, s41, s64
	s_nop 0
	global_load_lds_dwordx4 v138, s[42:43]
	s_cmp_lg_u32 s65, 7
	s_cbranch_scc1 .Lhg_nov_a
	s_add_i32 m0, s41, 0xf600
	s_nop 0
	global_load_lds_dwordx4 v139, s[42:43]
.Lhg_nov_a:
	s_waitcnt lgkmcnt(4)
	v_perm_b32 v0, v156, v156, v151
	v_perm_b32 v1, v157, v157, v151
	v_perm_b32 v3, v158, v158, v151
	v_perm_b32 v56, v159, v159, v151
	v_exp_f32_e32 v81, v0
	v_exp_f32_e32 v83, v1
	v_exp_f32_e32 v87, v3
	v_exp_f32_e32 v54, v56
	v_add_f32_e32 v1, v0, v1
	v_add_f32_e32 v3, v1, v3
	v_add_f32_e32 v63, v3, v56
	v_mov_b32_e32 v146, v63
	v_mov_b32_e32 v147, v63
	v_sub_f32_e32 v81, 1.0, v81
	v_sub_f32_e32 v83, 1.0, v83
	v_permlane16_swap_b32_e32 v146, v147
	v_sub_f32_e32 v87, 1.0, v87
	v_add_f32_e32 v148, v146, v147
	v_mov_b32_e32 v149, v148
	v_and_b32_e32 v150, v146, v145
	s_nop 0
	v_permlane32_swap_b32_e32 v148, v149
	v_cndmask_b32_e64 v52, 0, v148, s[48:49]
	v_add_f32_e32 v52, v52, v150
	s_waitcnt lgkmcnt(0)
	v_perm_b32 v78, v160, v160, v151
	v_perm_b32 v62, v161, v161, v151
	v_perm_b32 v84, v162, v162, v151
	v_perm_b32 v88, v163, v163, v151
	v_add_f32_e32 v0, v0, v52
	v_exp_f32_e32 v80, v0
	v_exp_f32_e64 v79, -v0
	v_add_f32_e32 v1, v1, v52
	v_sub_f32_e32 v91, 1.0, v54
	v_add_f32_e32 v54, v63, v52
	v_exp_f32_e32 v82, v1
	v_exp_f32_e64 v63, -v1
	v_add_f32_e32 v3, v3, v52
	v_pk_mul_f32 v[78:79], v[80:81], v[78:79]
	v_exp_f32_e32 v86, v3
	v_exp_f32_e64 v85, -v3
	v_cvt_pk_bf16_f32 v170, v78, v79
	v_exp_f32_e32 v90, v54
	v_exp_f32_e64 v89, -v54
	v_add_u32_e32 v184, v26, v43
	v_pk_mul_f32 v[62:63], v[82:83], v[62:63]
	v_add_f32_e32 v0, v148, v149
	v_cvt_pk_bf16_f32 v171, v62, v63
	v_pk_mul_f32 v[62:63], v[86:87], v[84:85]
	v_and_b32_e32 v184, -4, v184
	v_cvt_pk_bf16_f32 v172, v62, v63
	v_pk_mul_f32 v[78:79], v[90:91], v[88:89]
	v_add_u32_e32 v184, v184, v186
	v_cvt_pk_bf16_f32 v173, v78, v79
	v_perm_b32 v62, v171, v170, s17
	v_perm_b32 v63, v173, v172, s17
	v_cndmask_b32_e64 v174, v170, v172, s[44:45]
	v_cndmask_b32_e64 v175, v171, v173, s[44:45]
	v_cndmask_b32_e64 v176, v172, v170, s[44:45]
	v_cndmask_b32_e64 v177, v173, v171, s[44:45]
	v_add_u32_e32 v185, 0x1100, v184
	v_mov_b32_dpp v178, v174 quad_perm:[1,0,3,2] row_mask:0xf bank_mask:0xf
	v_mov_b32_dpp v179, v175 quad_perm:[1,0,3,2] row_mask:0xf bank_mask:0xf
	v_add_u32_e32 v1, v27, v37
	v_perm_b32 v180, v176, v178, v154
	v_perm_b32 v181, v177, v179, v154
	v_perm_b32 v182, v176, v178, v155
	v_perm_b32 v183, v177, v179, v155
	ds_write2_b32 v184, v180, v181 offset1:68
	ds_write2_b32 v185, v182, v183 offset1:68
	ds_write_b64 v1, v[62:63] offset:23040
	s_and_saveexec_b64 s[14:15], s[46:47]
	s_cbranch_execz .LBB0_627
	s_waitcnt lgkmcnt(9)
	v_exp_f32_e32 v0, v0
	v_add_u32_e32 v1, v27, v45
	ds_write_b32 v1, v0 offset:28160

; #define LAS __attribute__((address_space(3)))
; __device__ __forceinline__ unsigned cvtpk(float lo, float hi) { f32x2_t v = {lo, hi}; bf16x2_t b = __builtin_convertvector(v, bf16x2_t); return __builtin_bit_cast(unsigned, b); }
; __device__ __forceinline__ void prep(const Raw& Rin, LAS unsigned char* buf, int lane, int kch, int tq, bool isv, int vv, int vtq) {
;     Raw R = Rin; const bool kodd = kch & 1, vodd = vv & 1;
; #pragma unroll
;     for (int i = 0; i < 4; ++i) { asm volatile("" : "+v"(R.q[i])); asm volatile("" : "+v"(R.f[i])); asm volatile("" : "+v"(R.v[i])); }
;     float qv[4], kk[4], c[4]; float run = 0.f;
; #pragma unroll
;     for (int i = 0; i < 4; ++i) {
;         qv[i] = __uint_as_float(kodd ? (R.q[i] & 0xffff0000u) : (R.q[i] << 16));
;         const float l2 = __uint_as_float(kodd ? (R.f[i] & 0xffff0000u) : (R.f[i] << 16));
;         kk[i] = 1.f - __builtin_amdgcn_exp2f(l2);
;         run += l2; c[i] = run;
;     }
;     const float p1 = __shfl(run, (lane - 16) & 63), p2 = __shfl(run, (lane - 32) & 63), p3 = __shfl(run, (lane - 48) & 63);
;     const float off = (tq >= 1 ? p1 : 0.f) + (tq >= 2 ? p2 : 0.f) + (tq >= 3 ? p3 : 0.f);
;     const float btot = __shfl(off + run, 48 + (lane & 15));
;     unsigned short kf[4];
; #pragma unroll
;     for (int i = 0; i < 4; ++i) {
;         const float bt = off + c[i];
;         const float qf = qv[i] * __builtin_amdgcn_exp2f(bt), kfv = kk[i] * __builtin_amdgcn_exp2f(-bt);
;         const unsigned pk = cvtpk(qf, kfv);
;         *(LAS unsigned short*)(buf + OFF_QF + (4 * tq + i) * STR + kch * 2) = (unsigned short)(pk & 0xffffu);
;         kf[i] = (unsigned short)(pk >> 16);
;         *(LAS unsigned short*)(buf + OFF_KF + (4 * tq + i) * STR + kch * 2) = kf[i];
;     }
;     *(LAS u32x2*)(buf + OFF_KFT + kch * 32 + tq * 8) = (u32x2){(unsigned)kf[0] | ((unsigned)kf[1] << 16), (unsigned)kf[2] | ((unsigned)kf[3] << 16)};
;     if (tq == 0) *(LAS float*)(buf + OFF_D + kch * 4) = __builtin_amdgcn_exp2f(btot);
.Lhg_wd_a:
	s_barrier
	s_cmpk_gt_u32 s7, 0x7d
	s_cbranch_scc1 .LBB0_642
	s_add_i32 s41, s7, 2
	s_and_b32 s41, s41, 3
	s_mul_i32 s41, s41, 9792
	v_add_u32_e32 v140, s41, v136
	v_add_u32_e32 v141, s41, v137
	v_add_u32_e32 v153, 0x1100, v140
	ds_read2_b32 v[156:157], v153 offset1:64
	ds_read2_b32 v[158:159], v153 offset0:128 offset1:192
	ds_read2_b32 v[160:161], v140 offset1:64
	ds_read2_b32 v[162:163], v140 offset0:128 offset1:192
	ds_read2_b32 v[166:167], v141 offset1:16
	ds_read2_b32 v[168:169], v141 offset0:32 offset1:48
	s_add_i32 s41, s7, 5
	s_min_u32 s41, s41, 0x7f
	s_mul_i32 s41, s41, 0x1d400
	s_add_u32 s42, s38, s41
	s_addc_u32 s43, s39, 0
	s_add_i32 s41, s7, 1
	s_and_b32 s41, s41, 3
	s_mul_i32 s41, s41, 9792
	s_add_i32 m0, s41, s64
	s_nop 0
	global_load_lds_dwordx4 v138, s[42:43]
	s_cmp_lg_u32 s65, 7
	s_cbranch_scc1 .Lhg_nov_b
	s_add_i32 m0, s41, 0xf600
	s_nop 0
	global_load_lds_dwordx4 v139, s[42:43]
.Lhg_nov_b:
	s_waitcnt lgkmcnt(4)
	v_perm_b32 v0, v156, v156, v151
	v_perm_b32 v1, v157, v157, v151
	v_perm_b32 v3, v158, v158, v151
	v_perm_b32 v72, v159, v159, v151
	v_exp_f32_e32 v81, v0
	v_exp_f32_e32 v85, v1
	v_exp_f32_e32 v87, v3
	v_exp_f32_e32 v68, v72
	v_add_f32_e32 v1, v0, v1
	v_add_f32_e32 v3, v1, v3
	v_add_f32_e32 v75, v3, v72
	v_mov_b32_e32 v146, v75
	v_mov_b32_e32 v147, v75
	v_sub_f32_e32 v81, 1.0, v81
	v_sub_f32_e32 v85, 1.0, v85
	v_permlane16_swap_b32_e32 v146, v147
	v_sub_f32_e32 v87, 1.0, v87
	v_add_f32_e32 v148, v146, v147
	v_mov_b32_e32 v149, v148
	v_and_b32_e32 v150, v146, v145
	s_nop 0
	v_permlane32_swap_b32_e32 v148, v149
	v_cndmask_b32_e64 v72, 0, v148, s[48:49]
	v_add_f32_e32 v72, v72, v150
	s_waitcnt lgkmcnt(0)
	v_perm_b32 v66, v160, v160, v151
	v_perm_b32 v82, v161, v161, v151
	v_perm_b32 v74, v162, v162, v151
	v_perm_b32 v76, v163, v163, v151
	v_add_f32_e32 v0, v0, v72
	v_exp_f32_e32 v80, v0
	v_exp_f32_e64 v67, -v0
	v_add_f32_e32 v1, v1, v72
	v_exp_f32_e32 v84, v1
	v_exp_f32_e64 v83, -v1
	v_sub_f32_e32 v89, 1.0, v68
	v_add_f32_e32 v68, v75, v72
	v_add_f32_e32 v3, v3, v72
	v_pk_mul_f32 v[66:67], v[80:81], v[66:67]
	v_exp_f32_e32 v86, v3
	v_exp_f32_e64 v75, -v3
	v_exp_f32_e32 v88, v68
	v_exp_f32_e64 v77, -v68
	v_cvt_pk_bf16_f32 v170, v66, v67
	v_add_f32_e32 v0, v148, v149
	v_add_u32_e32 v184, v36, v43
	v_pk_mul_f32 v[66:67], v[84:85], v[82:83]
	v_and_b32_e32 v184, -4, v184
	v_cvt_pk_bf16_f32 v171, v66, v67
	v_pk_mul_f32 v[66:67], v[86:87], v[74:75]
	v_pk_mul_f32 v[74:75], v[88:89], v[76:77]
	v_add_u32_e32 v184, v184, v187
	v_cvt_pk_bf16_f32 v172, v66, v67
	v_cvt_pk_bf16_f32 v173, v74, v75
	v_perm_b32 v66, v171, v170, s17
	v_perm_b32 v67, v173, v172, s17
	v_cndmask_b32_e64 v174, v170, v172, s[44:45]
	v_cndmask_b32_e64 v175, v171, v173, s[44:45]
	v_cndmask_b32_e64 v176, v172, v170, s[44:45]
	v_cndmask_b32_e64 v177, v173, v171, s[44:45]
	v_add_u32_e32 v185, 0x1100, v184
	v_mov_b32_dpp v178, v174 quad_perm:[1,0,3,2] row_mask:0xf bank_mask:0xf
	v_mov_b32_dpp v179, v175 quad_perm:[1,0,3,2] row_mask:0xf bank_mask:0xf
	v_perm_b32 v180, v176, v178, v154
	v_perm_b32 v181, v177, v179, v154
	v_perm_b32 v182, v176, v178, v155
	v_perm_b32 v183, v177, v179, v155
	ds_write2_b32 v184, v180, v181 offset1:68
	ds_write2_b32 v185, v182, v183 offset1:68
	ds_write_b64 v38, v[66:67] offset:8704
	s_and_saveexec_b64 s[14:15], s[46:47]
	s_cbranch_execz .LBB0_638
	s_waitcnt lgkmcnt(9)
	v_exp_f32_e32 v0, v0
	v_add_u32_e32 v1, v27, v45
	ds_write_b32 v1, v0 offset:13824
